# diff-attention unit prologue: four Q fragment loads batched (was 4 serialized round trips), K1 tile issued with K0/V0
# baseline (speedup 1.0000x reference)
; #define LAS __attribute__((address_space(3)))
; #define DIFF_GLOADK(t) do { _Pragma("unroll") for (int i = 0; i < 2; ++i) kreg[i] = *(const u32x4*)(sbase + O_DK + (size_t)(64 * (t) + 32 * i) * QP); } while (0)
; #define DIFF_GLOADV(t) do { _Pragma("unroll") for (int i = 0; i < 2; ++i) vreg[i] = *(const u32x4*)(sbase + O_DV + (size_t)(64 * (t) + 32 * i) * QP); } while (0)
; #define DIFF_LSTOREK(buf) do { _Pragma("unroll") for (int i = 0; i < 2; ++i) *(LAS u32x4*)(lds + (buf) * BUFB + KOFF + (srow + 32 * i) * 272 + sch * 16) = kreg[i]; } while (0)
; #define DIFF_LSTOREV(buf) do { _Pragma("unroll") for (int i = 0; i < 2; ++i) *(LAS u32x4*)(lds + (buf) * BUFB + VOFF + (srow + 32 * i) * DVS + sch * 16) = vreg[i]; } while (0)
; __device__ __forceinline__ void diff_unit(const Params& P, int l, int b, int h, int qb, float lam, float lam_init, LAS unsigned char* lds, bool dry = false) {
;     ...
;     { const bf16_t* Qw = proj + O_DQ + (rowb + q0 + wq * 32 + r32) * QP + h * 128 + map * 64;
; #pragma unroll
;       for (int d0 = 0; d0 < 4; ++d0) *(LAS bf16x8*)(qlds + d0 * 32) = *(const bf16x8*)(Qw + d0 * 16 + hi * 8); }
;     ...
;     DIFF_GLOADK(0); DIFF_GLOADV(0); DIFF_LSTOREK(0); DIFF_LSTOREV(0);
;     DIFF_GLOADK(1); DIFF_LSTOREK(1);
.LBB0_392:
	s_or_b64 exec, exec, s[4:5]
	s_ashr_i32 s6, s73, 6
	s_ashr_i32 s48, s57, 5
	s_and_b32 s74, s6, 3
	s_mulk_i32 s6, 0x1200
	s_and_b32 s71, s57, 7
	s_ashr_i32 s49, s48, 31
	s_add_i32 s6, s6, 0
	s_ashr_i32 s78, s73, 8
	s_lshl_b64 s[4:5], s[48:49], 11
	s_lshl_b32 s7, s71, 7
	s_add_i32 s6, s6, 0x13800
	s_add_u32 s90, s2, 0xee00000
	s_addc_u32 s91, s3, 0
	s_lshl_b32 s81, s74, 5
	s_or_b32 s52, s81, s7
	s_waitcnt vmcnt(0)
	v_and_b32_e32 v167, 31, v160
	s_or_b32 s50, s4, s52
	v_or_b32_e32 v2, s50, v167
	v_mov_b32_e32 v3, s5
	v_mov_b32_e32 v1, s6
	s_movk_i32 s6, 0x90
	v_lshlrev_b64 v[2:3], 10, v[2:3]
	v_mad_u32_u24 v1, v167, s6, v1
	v_lshl_add_u64 v[2:3], s[90:91], 0, v[2:3]
	s_lshl_b32 s96, s70, 8
	s_lshl_b32 s6, s78, 6
	v_bfe_u32 v166, v160, 5, 1
	v_lshl_add_u64 v[2:3], v[2:3], 0, s[96:97]
	s_ashr_i32 s7, s6, 31
	v_lshlrev_b32_e32 v156, 4, v166
	v_lshl_add_u64 v[2:3], s[6:7], 1, v[2:3]
	v_mov_b32_e32 v157, v0
	v_lshl_add_u64 v[6:7], v[2:3], 0, v[156:157]
	global_load_dwordx4 v[2:5], v[6:7], off
	global_load_dwordx4 v[148:151], v[6:7], off offset:32
	global_load_dwordx4 v[152:155], v[6:7], off offset:64
	global_load_dwordx4 v[16:19], v[6:7], off offset:96
	v_add_u32_e32 v35, v1, v156
	v_ashrrev_i32_e32 v162, 4, v160
	v_ashrrev_i32_e32 v163, 31, v162
	v_lshlrev_b32_e32 v1, 4, v160
	v_and_b32_e32 v158, 0xf0, v1
	v_mov_b32_e32 v159, v0
	s_mov_b32 s6, 0x10e00000
	v_add_u32_e32 v175, 0, v158
	v_or_b32_e32 v168, s52, v167
	s_cmpk_lt_u32 s52, 0xb0
	v_lshlrev_b32_e32 v157, 2, v166
	s_waitcnt vmcnt(0) lgkmcnt(0)
	ds_write_b128 v35, v[2:5]
	ds_write_b128 v35, v[148:151] offset:32
	ds_write_b128 v35, v[152:155] offset:64
	ds_write_b128 v35, v[16:19] offset:96
	v_lshl_add_u64 v[2:3], s[4:5], 0, v[162:163]
	v_lshlrev_b64 v[2:3], 10, v[2:3]
	v_lshl_add_u64 v[2:3], s[2:3], 0, v[2:3]
	v_lshl_add_u64 v[2:3], v[2:3], 0, s[96:97]
	v_lshl_add_u64 v[14:15], v[2:3], 0, v[158:159]
	v_add_co_u32_e32 v2, vcc, s6, v14
	s_mov_b32 s6, 0x10e08000
	s_nop 0
	v_addc_co_u32_e32 v3, vcc, 0, v15, vcc
	v_add_co_u32_e32 v6, vcc, s6, v14
	s_mov_b32 s6, 0x12e00000
	s_nop 0
	v_addc_co_u32_e32 v7, vcc, 0, v15, vcc
	v_add_co_u32_e32 v10, vcc, s6, v14
	s_mov_b32 s6, 0x12e08000
	s_nop 0
	v_addc_co_u32_e32 v11, vcc, 0, v15, vcc
	v_add_co_u32_e32 v16, vcc, s6, v14
	global_load_dwordx4 v[2:5], v[2:3], off
	s_nop 0
	v_addc_co_u32_e32 v17, vcc, 0, v15, vcc
	global_load_dwordx4 v[6:9], v[6:7], off
	s_movk_i32 s6, 0x110
	global_load_dwordx4 v[10:13], v[10:11], off
	v_mul_lo_u32 v159, v162, s6
	global_load_dwordx4 v[16:19], v[16:17], off
	s_movk_i32 s6, 0x140
	v_mul_lo_u32 v174, v162, s6
	v_add_u32_e32 v176, v175, v159
	v_add_u32_e32 v1, 0x2800, v174
	s_mov_b32 s6, 0x10e10000
	v_add_u32_e32 v177, v175, v174
	v_add_u32_e32 v178, v175, v1
	v_add_co_u32_e32 v148, vcc, s6, v14
	s_nop 1
	v_addc_co_u32_e32 v149, vcc, 0, v15, vcc
	global_load_dwordx4 v[148:151], v[148:149], off
	v_add_co_u32_e32 v152, vcc, 0x10e18000, v14
	s_nop 1
	v_addc_co_u32_e32 v153, vcc, 0, v15, vcc
	global_load_dwordx4 v[152:155], v[152:153], off
	v_readlane_b32 s6, v255, 8
	s_waitcnt vmcnt(0) lgkmcnt(0)
	ds_write_b128 v176, v[2:5]
	ds_write_b128 v176, v[6:9] offset:8704
	ds_write_b128 v177, v[10:13] offset:17408
	ds_write_b128 v178, v[16:19] offset:17408
	v_mov_b32_e32 v1, s6
	ds_write_b128 v176, v[148:151] offset:37888
	ds_write_b128 v176, v[152:155] offset:46592
	s_waitcnt lgkmcnt(0)
	s_barrier
	ds_read_b32 v34, v1
	s_cbranch_scc0 .LBB0_394
	v_or_b32_e32 v5, 2, v157
	v_or_b32_e32 v7, 3, v157
	v_sub_u32_e32 v1, v168, v157
	v_xad_u32 v3, v157, -1, v168
	v_sub_u32_e32 v5, v168, v5
	v_sub_u32_e32 v7, v168, v7
	v_med3_i32 v2, v1, 0, v223
	v_max_i32_e32 v1, 32, v1
	v_med3_i32 v4, v3, 0, v223
	v_max_i32_e32 v3, 32, v3
	v_med3_i32 v6, v5, 0, v223
	v_max_i32_e32 v5, 32, v5
	v_med3_i32 v8, v7, 0, v223
	v_max_i32_e32 v7, 32, v7
	v_subrev_u32_e32 v1, 32, v1
	v_subrev_u32_e32 v3, 32, v3
	v_subrev_u32_e32 v5, 32, v5
	v_subrev_u32_e32 v7, 32, v7
	s_add_i32 s6, 0, 0x13000
	v_min_u32_e32 v1, 0x7f, v1
	v_min_u32_e32 v3, 0x7f, v3
	v_min_u32_e32 v5, 0x7f, v5
	v_min_u32_e32 v7, 0x7f, v7
	v_lshl_add_u32 v2, v2, 2, s6
	v_lshl_add_u32 v1, v1, 2, s6
	v_lshl_add_u32 v3, v3, 2, s6
	v_lshl_add_u32 v5, v5, 2, s6
	v_lshl_add_u32 v7, v7, 2, s6
	v_lshl_add_u32 v4, v4, 2, s6
	v_lshl_add_u32 v6, v6, 2, s6
	v_lshl_add_u32 v8, v8, 2, s6
	ds_read_b32 v36, v2
	ds_read_b32 v16, v1
	ds_read_b32 v37, v4
	ds_read_b32 v17, v3
	ds_read_b32 v38, v6
	ds_read_b32 v18, v5
	ds_read_b32 v39, v8
	ds_read_b32 v19, v7
	v_or_b32_e32 v1, 8, v157
	v_or_b32_e32 v3, 9, v157
	v_or_b32_e32 v5, 10, v157
	v_or_b32_e32 v7, 11, v157
	v_sub_u32_e32 v1, v168, v1
	v_sub_u32_e32 v3, v168, v3
	v_sub_u32_e32 v5, v168, v5
	v_sub_u32_e32 v7, v168, v7
	v_med3_i32 v2, v1, 0, v223
	v_max_i32_e32 v1, 32, v1
	v_med3_i32 v4, v3, 0, v223
	v_max_i32_e32 v3, 32, v3
	v_med3_i32 v6, v5, 0, v223
	v_max_i32_e32 v5, 32, v5
	v_med3_i32 v8, v7, 0, v223
	v_max_i32_e32 v7, 32, v7
	v_subrev_u32_e32 v1, 32, v1
	v_subrev_u32_e32 v3, 32, v3
	v_subrev_u32_e32 v5, 32, v5
	v_subrev_u32_e32 v7, 32, v7
	v_min_u32_e32 v1, 0x7f, v1
	v_min_u32_e32 v3, 0x7f, v3
	v_min_u32_e32 v5, 0x7f, v5
	v_min_u32_e32 v7, 0x7f, v7
	v_lshl_add_u32 v2, v2, 2, s6
	v_lshl_add_u32 v1, v1, 2, s6
	v_lshl_add_u32 v3, v3, 2, s6
	v_lshl_add_u32 v5, v5, 2, s6
	v_lshl_add_u32 v7, v7, 2, s6
	v_lshl_add_u32 v4, v4, 2, s6
	v_lshl_add_u32 v6, v6, 2, s6
	v_lshl_add_u32 v8, v8, 2, s6
	ds_read_b32 v40, v2
	ds_read_b32 v20, v1
	ds_read_b32 v41, v4
	ds_read_b32 v21, v3
	ds_read_b32 v42, v6
	ds_read_b32 v22, v5
	ds_read_b32 v43, v8
	ds_read_b32 v23, v7
	v_or_b32_e32 v1, 16, v157
	v_or_b32_e32 v3, 17, v157
	v_or_b32_e32 v5, 18, v157
	v_or_b32_e32 v7, 19, v157
	v_sub_u32_e32 v1, v168, v1
	v_sub_u32_e32 v3, v168, v3
	v_sub_u32_e32 v5, v168, v5
	v_sub_u32_e32 v7, v168, v7
	v_med3_i32 v2, v1, 0, v223
	v_max_i32_e32 v1, 32, v1
	v_med3_i32 v4, v3, 0, v223
	v_max_i32_e32 v3, 32, v3
	v_med3_i32 v6, v5, 0, v223
	v_max_i32_e32 v5, 32, v5
	v_med3_i32 v8, v7, 0, v223
	v_max_i32_e32 v7, 32, v7
	v_subrev_u32_e32 v1, 32, v1
	v_subrev_u32_e32 v3, 32, v3
	v_subrev_u32_e32 v5, 32, v5
	v_subrev_u32_e32 v7, 32, v7
	v_min_u32_e32 v1, 0x7f, v1
	v_min_u32_e32 v3, 0x7f, v3
	v_min_u32_e32 v5, 0x7f, v5
	v_min_u32_e32 v7, 0x7f, v7
	v_lshl_add_u32 v2, v2, 2, s6
	v_lshl_add_u32 v1, v1, 2, s6
	v_lshl_add_u32 v3, v3, 2, s6
	v_lshl_add_u32 v5, v5, 2, s6
	v_lshl_add_u32 v7, v7, 2, s6
	v_lshl_add_u32 v4, v4, 2, s6
	v_lshl_add_u32 v6, v6, 2, s6
	v_lshl_add_u32 v8, v8, 2, s6
	ds_read_b32 v44, v2
	ds_read_b32 v24, v1
	ds_read_b32 v45, v4
	ds_read_b32 v25, v3
	ds_read_b32 v46, v6
	ds_read_b32 v26, v5
	ds_read_b32 v47, v8
	ds_read_b32 v27, v7
	v_or_b32_e32 v1, 24, v157
	v_or_b32_e32 v3, 25, v157
	v_or_b32_e32 v5, 26, v157
	v_or_b32_e32 v7, 27, v157
	v_sub_u32_e32 v1, v168, v1
	v_sub_u32_e32 v3, v168, v3
	v_sub_u32_e32 v5, v168, v5
	v_sub_u32_e32 v7, v168, v7
	v_med3_i32 v2, v1, 0, v223
	v_max_i32_e32 v1, 32, v1
	v_med3_i32 v4, v3, 0, v223
	v_max_i32_e32 v3, 32, v3
	v_med3_i32 v6, v5, 0, v223
	v_max_i32_e32 v5, 32, v5
	v_med3_i32 v8, v7, 0, v223
	v_max_i32_e32 v7, 32, v7
	v_subrev_u32_e32 v1, 32, v1
	v_subrev_u32_e32 v3, 32, v3
	v_subrev_u32_e32 v5, 32, v5
	v_subrev_u32_e32 v7, 32, v7
	v_lshl_add_u32 v2, v2, 2, s6
	v_min_u32_e32 v1, 0x7f, v1
	v_min_u32_e32 v3, 0x7f, v3
	v_min_u32_e32 v5, 0x7f, v5
	v_min_u32_e32 v7, 0x7f, v7
	v_lshl_add_u32 v1, v1, 2, s6
	v_lshl_add_u32 v4, v4, 2, s6
	v_lshl_add_u32 v3, v3, 2, s6
	v_lshl_add_u32 v6, v6, 2, s6
	v_lshl_add_u32 v5, v5, 2, s6
	v_lshl_add_u32 v8, v8, 2, s6
	v_lshl_add_u32 v7, v7, 2, s6
	ds_read_b32 v48, v2
	ds_read_b32 v28, v1
	ds_read_b32 v49, v4
	ds_read_b32 v29, v3
	ds_read_b32 v50, v6
	ds_read_b32 v30, v5
	ds_read_b32 v51, v8
	ds_read_b32 v31, v7
	s_cbranch_execz .LBB0_395
	s_branch .LBB0_396

; #define LAS __attribute__((address_space(3)))
; #define DIFF_QK(P0, P1, kt) do { bf16x8 qf[4]; _Pragma("unroll") for (int d0 = 0; d0 < 4; ++d0) qf[d0] = *(const LAS bf16x8*)(qlds + d0 * 32); attn_qk(P0, P1, kt, 272, qf, r32, hi); } while (0)
; #define DIFF_GLOADK(t) do { _Pragma("unroll") for (int i = 0; i < 2; ++i) kreg[i] = *(const u32x4*)(sbase + O_DK + (size_t)(64 * (t) + 32 * i) * QP); } while (0)
; #define DIFF_GLOADV(t) do { _Pragma("unroll") for (int i = 0; i < 2; ++i) vreg[i] = *(const u32x4*)(sbase + O_DV + (size_t)(64 * (t) + 32 * i) * QP); } while (0)
; #define DIFF_LSTOREK(buf) do { _Pragma("unroll") for (int i = 0; i < 2; ++i) *(LAS u32x4*)(lds + (buf) * BUFB + KOFF + (srow + 32 * i) * 272 + sch * 16) = kreg[i]; } while (0)
; #define DIFF_LSTOREV(buf) do { _Pragma("unroll") for (int i = 0; i < 2; ++i) *(LAS u32x4*)(lds + (buf) * BUFB + VOFF + (srow + 32 * i) * DVS + sch * 16) = vreg[i]; } while (0)
; __device__ __forceinline__ void diff_unit(const Params& P, int l, int b, int h, int qb, float lam, float lam_init, LAS unsigned char* lds, bool dry = false) {
;     ...
;     { const bf16_t* Qw = proj + O_DQ + (rowb + q0 + wq * 32 + r32) * QP + h * 128 + map * 64;
; #pragma unroll
;       for (int d0 = 0; d0 < 4; ++d0) *(LAS bf16x8*)(qlds + d0 * 32) = *(const bf16x8*)(Qw + d0 * 16 + hi * 8); }
;     ...
;     DIFF_GLOADK(0); DIFF_GLOADV(0); DIFF_LSTOREK(0); DIFF_LSTOREV(0);
;     DIFF_GLOADK(1); DIFF_LSTOREK(1);
;     __syncthreads();
;     const float b31 = bt[127];
;     f32x16 s0, s1, n0 = {}, n1 = {};
;     DIFF_INIT(s0, s1, 0); DIFF_QK(s0, s1, lds + KOFF + map * 128);
.LBB0_495:
	s_or_b64 exec, exec, s[6:7]
	s_ashr_i32 s6, s52, 6
	s_and_b32 s7, s52, 0x3fffffc0
	s_and_b32 s53, s6, 3
	s_lshl_b32 s7, s7, 2
	s_mulk_i32 s6, 0x1200
	s_xor_b32 s9, s71, 15
	s_add_i32 s55, s7, 0
	s_add_i32 s6, s6, 0
	s_ashr_i32 s54, s52, 8
	s_lshl_b32 s8, s9, 7
	s_add_i32 s55, s55, 0x12800
	s_add_i32 s10, s6, 0x13800
	s_add_u32 s50, s2, 0xee00000
	s_addc_u32 s51, s3, 0
	s_lshl_b32 s71, s53, 5
	s_or_b32 s70, s71, s8
	v_and_b32_e32 v186, 31, v62
	s_or_b32 s90, s4, s70
	v_or_b32_e32 v2, s90, v186
	v_mov_b32_e32 v3, s5
	v_lshlrev_b64 v[2:3], 10, v[2:3]
	v_lshl_add_u64 v[2:3], s[50:51], 0, v[2:3]
	s_lshl_b32 s96, s82, 1
	s_lshl_b32 s6, s54, 6
	v_bfe_u32 v1, v62, 5, 1
	v_lshl_add_u64 v[2:3], v[2:3], 0, s[96:97]
	s_ashr_i32 s7, s6, 31
	v_lshlrev_b32_e32 v188, 4, v1
	v_lshl_add_u64 v[2:3], s[6:7], 1, v[2:3]
	v_mov_b32_e32 v189, v0
	v_lshl_add_u64 v[6:7], v[2:3], 0, v[188:189]
	global_load_dwordx4 v[2:5], v[6:7], off
	global_load_dwordx4 v[102:105], v[6:7], off offset:32
	global_load_dwordx4 v[106:109], v[6:7], off offset:64
	global_load_dwordx4 v[50:53], v[6:7], off offset:96
	v_mov_b32_e32 v8, s10
	s_movk_i32 s6, 0x90
	v_mad_u32_u24 v8, v186, s6, v8
	v_add_u32_e32 v199, v8, v188
	v_ashrrev_i32_e32 v100, 4, v62
	v_ashrrev_i32_e32 v101, 31, v100
	v_mov_b32_e32 v157, v0
	s_movk_i32 s6, 0x110
	v_mul_lo_u32 v160, v100, s6
	s_lshl_b32 s74, s9, 1
	s_mov_b32 s9, 0x10e20000
	v_and_b32_e32 v189, 63, v62
	v_lshlrev_b32_e32 v195, 2, v1
	s_lshl_b64 s[12:13], s[48:49], 21
	s_mov_b32 s73, 2
	s_mov_b32 s10, 4
	s_mov_b32 s91, s5
	v_mul_u32_u24_e32 v176, 0x110, v186
	s_add_i32 s48, s70, 0xffffff00
	s_movk_i32 s49, 0x100
	v_lshlrev_b32_e32 v6, 4, v62
	v_and_b32_e32 v156, 0xf0, v6
	v_lshl_add_u64 v[6:7], s[4:5], 0, v[100:101]
	v_lshlrev_b64 v[6:7], 10, v[6:7]
	v_lshl_add_u64 v[6:7], s[2:3], 0, v[6:7]
	v_lshl_add_u64 v[6:7], v[6:7], 0, s[96:97]
	v_lshl_add_u64 v[82:83], v[6:7], 0, v[156:157]
	s_mov_b32 s4, 0x10e00000
	v_add_co_u32_e32 v6, vcc, s4, v82
	s_mov_b32 s4, 0x10e08000
	s_nop 0
	v_addc_co_u32_e32 v7, vcc, 0, v83, vcc
	v_add_co_u32_e32 v8, vcc, s4, v82
	s_mov_b32 s4, 0x12e00000
	s_nop 0
	v_addc_co_u32_e32 v9, vcc, 0, v83, vcc
	v_add_co_u32_e32 v10, vcc, s4, v82
	s_mov_b32 s4, 0x12e08000
	s_nop 0
	v_addc_co_u32_e32 v11, vcc, 0, v83, vcc
	v_add_co_u32_e32 v14, vcc, s4, v82
	s_movk_i32 s4, 0x140
	s_nop 0
	v_addc_co_u32_e32 v15, vcc, 0, v83, vcc
	v_mul_lo_u32 v161, v100, s4
	v_add_u32_e32 v162, 0, v156
	v_add_u32_e32 v18, 0x2800, v161
	s_mov_b32 s4, 0x10e10000
	v_add_u32_e32 v173, v162, v18
	v_add_co_u32_e32 v18, vcc, s4, v82
	v_add_u32_e32 v163, v162, v160
	s_nop 0
	v_addc_co_u32_e32 v19, vcc, 0, v83, vcc
	s_mov_b32 s4, 0x10e18000
	v_add_u32_e32 v172, v162, v161
	v_add_co_u32_e32 v20, vcc, s4, v82
	v_readlane_b32 s4, v255, 8
	s_nop 0
	v_addc_co_u32_e32 v21, vcc, 0, v83, vcc
	s_add_i32 s5, s74, -4
	s_waitcnt vmcnt(0) lgkmcnt(0)
	ds_write_b128 v199, v[2:5]
	ds_write_b128 v199, v[102:105] offset:32
	ds_write_b128 v199, v[106:109] offset:64
	ds_write_b128 v199, v[50:53] offset:96
	global_load_dwordx4 v[2:5], v[6:7], off
	s_nop 0
	global_load_dwordx4 v[6:9], v[8:9], off
	s_nop 0
	global_load_dwordx4 v[10:13], v[10:11], off
	s_nop 0
	global_load_dwordx4 v[14:17], v[14:15], off
	global_load_dwordx4 v[102:105], v[20:21], off
	global_load_dwordx4 v[18:21], v[18:19], off
	s_waitcnt vmcnt(0) lgkmcnt(0)
	ds_write_b128 v163, v[2:5]
	ds_write_b128 v163, v[6:9] offset:8704
	ds_write_b128 v172, v[10:13] offset:17408
	ds_write_b128 v173, v[14:17] offset:17408
	v_mov_b32_e32 v10, s4
	s_lshl_b32 s4, s54, 7
	s_add_i32 s4, s4, 0
	v_mov_b32_e32 v11, s4
	v_mad_u32_u24 v11, v186, s6, v11
	v_add_u32_e32 v174, v11, v188
	v_cmp_gt_u32_e64 s[6:7], 32, v189
	ds_write_b128 v163, v[18:21] offset:37888
	ds_write_b128 v163, v[102:105] offset:46592
	s_waitcnt lgkmcnt(0)
	s_barrier
	ds_read_b32 v66, v10
	ds_read_b128 v[102:105], v199
	ds_read_b128 v[106:109], v199 offset:32
	ds_read_b128 v[2:5], v174 offset:37888
	ds_read_b128 v[6:9], v174
	ds_read_b128 v[50:53], v174 offset:46688
	s_waitcnt lgkmcnt(5)
	v_mov_b32_e32 v67, v66
	v_mov_b32_e32 v68, v66
	v_mov_b32_e32 v69, v66
	v_mov_b32_e32 v70, v66
	v_mov_b32_e32 v71, v66
	v_mov_b32_e32 v72, v66
	v_mov_b32_e32 v73, v66
	v_mov_b32_e32 v74, v66
	v_mov_b32_e32 v75, v66
	v_mov_b32_e32 v76, v66
	v_mov_b32_e32 v77, v66
	v_mov_b32_e32 v78, v66
	v_mov_b32_e32 v79, v66
	v_mov_b32_e32 v80, v66
	v_mov_b32_e32 v81, v66
	s_waitcnt lgkmcnt(1)
	s_nop 0
	v_mfma_f32_32x32x16_bf16 v[18:33], v[6:9], v[102:105], v[66:81]
	ds_read_b128 v[6:9], v174 offset:8704
	ds_read_b128 v[58:61], v174 offset:96
	ds_read_b128 v[110:113], v174 offset:46592
	ds_read_b128 v[54:57], v174 offset:37984
	s_waitcnt lgkmcnt(3)
	v_mfma_f32_32x32x16_bf16 v[34:49], v[6:9], v[102:105], v[66:81]
	v_mfma_f32_32x32x16_bf16 v[84:99], v[2:5], v[102:105], v[66:81]
	v_mov_b64_e32 v[2:3], v[66:67]
	v_mov_b64_e32 v[4:5], v[68:69]
	v_mov_b64_e32 v[6:7], v[70:71]
	v_mov_b64_e32 v[8:9], v[72:73]
	v_mov_b64_e32 v[10:11], v[74:75]
	v_mov_b64_e32 v[12:13], v[76:77]
	v_mov_b64_e32 v[14:15], v[78:79]
	v_mov_b64_e32 v[16:17], v[80:81]
	ds_read_b128 v[68:71], v174 offset:32
	ds_read_b128 v[76:79], v174 offset:64
	s_waitcnt lgkmcnt(3)
	v_mfma_f32_32x32x16_bf16 v[2:17], v[110:113], v[102:105], v[2:17]
	v_and_b32_e32 v80, 16, v62
	v_lshrrev_b32_e32 v67, 2, v62
	v_and_or_b32 v67, v67, 3, v195
	v_mul_u32_u24_e32 v177, 0x140, v67
	s_waitcnt lgkmcnt(1)
	v_mfma_f32_32x32x16_bf16 v[18:33], v[68:71], v[106:109], v[18:33]
	ds_read_b128 v[68:71], v174 offset:8736
	ds_read_b128 v[102:105], v174 offset:8768
	s_waitcnt lgkmcnt(1)
; #define LAS __attribute__((address_space(3)))
; __device__ __forceinline__ float fast_exp2(float x) { return __builtin_amdgcn_exp2f(x); }
; template <int NDT, int VSTR> ...
;     if (domask) {
; #pragma unroll
;         for (int r = 0; r < 16; ++r) { const int kv = crow(r, hi); if (kv > qrel) p0[r] = -INFINITY; if (kv + 32 > qrel) p1[r] = -INFINITY; }
;     }
;     float ra = fmaxf(fmaxf(p0[0], p0[1]), p1[0]), rb = fmaxf(fmaxf(p0[2], p0[3]), p1[1]);
;     ra = fmaxf(fmaxf(ra, p1[2]), p1[3]);
; #pragma unroll
;     for (int r = 4; r < 16; r += 4) { ra = fmaxf(fmaxf(ra, p0[r]), p0[r + 1]); rb = fmaxf(fmaxf(rb, p0[r + 2]), p0[r + 3]); ra = fmaxf(fmaxf(ra, p1[r]), p1[r + 1]); rb = fmaxf(fmaxf(rb, p1[r + 2]), p1[r + 3]); }
;     const float rm = half_max(fmaxf(ra, rb));
;     if (first || __any(rm > 8.0f)) {
;         const float dl = first ? rm : fmaxf(rm, 0.f);
;         mref += dl;
; #pragma unroll
;         for (int r = 0; r < 16; ++r) { p0[r] -= dl; p1[r] -= dl; }
;         if (has_next) {
; #pragma unroll
;             for (int r = 0; r < 16; ++r) { n0[r] -= dl; n1[r] -= dl; } }
;         if (!first) {
;             const float alpha = fast_exp2(-dl);
;             lrun *= alpha;
;             if (hi == 0) wsf[r32] = alpha;
;             asm volatile("s_waitcnt lgkmcnt(0)" ::: "memory");
; #pragma unroll
;             for (int jj = 0; jj < 4; ++jj) { const f32x4 al = *(const LAS f32x4*)(wsf + 8 * jj + 4 * hi);
; #pragma unroll
;                 for (int d = 0; d < NDT; ++d) { o[d][4 * jj + 0] *= al.x; o[d][4 * jj + 1] *= al.y; o[d][4 * jj + 2] *= al.z; o[d][4 * jj + 3] *= al.w; } }
;             asm volatile("s_waitcnt lgkmcnt(0)" ::: "memory");
;         }
;     }
;     constexpr int PRE = (NDT == 2) ? 4 : 1;
;     const int lane_ = hi * 32 + r32;
;     const LAS unsigned char* vb = Vt + (4 * hi + ((lane_ & 15) >> 2)) * VSTR + (16 * ((lane_ >> 4) & 1) + 4 * (lane_ & 3)) * 2;
;     ...
;     bf16x8 vpre[PRE][NDT];
; #pragma unroll
;     for (int s = 0; s < PRE; ++s)
; #pragma unroll
;         for (int d = 0; d < NDT; ++d) vpre[s][d] = VFRAG(s, d);
;     float rs0 = 0.f, rs1 = 0.f;
; #pragma unroll
;     for (int r = 0; r < 16; ++r) { p0[r] = fast_exp2(p0[r]); p1[r] = fast_exp2(p1[r]); rs0 += p0[r]; rs1 += p1[r]; }
;     lrun += rs0 + rs1;
;     bf16x8 pa[4];
; #pragma unroll
;     for (int s = 0; s < 2; ++s) {
;         u32x4 w0, w1;
	v_mfma_f32_32x32x16_bf16 v[34:49], v[68:71], v[106:109], v[34:49]
	ds_read_b128 v[68:71], v174 offset:37920
	ds_read_b128 v[110:113], v174 offset:37952
	ds_read_b128 v[72:75], v174 offset:46624
	ds_read_b128 v[62:65], v199 offset:96
	s_waitcnt lgkmcnt(3)
	v_mfma_f32_32x32x16_bf16 v[84:99], v[68:71], v[106:109], v[84:99]
	ds_read_b128 v[68:71], v174 offset:46656
	s_waitcnt lgkmcnt(2)
	v_mfma_f32_32x32x16_bf16 v[2:17], v[72:75], v[106:109], v[2:17]
	ds_read_b128 v[72:75], v199 offset:64
	s_waitcnt lgkmcnt(0)
	v_mfma_f32_32x32x16_bf16 v[18:33], v[76:79], v[72:75], v[18:33]
	v_lshlrev_b32_e32 v78, 2, v186
	v_and_or_b32 v79, v78, 12, v80
	v_add_u32_e32 v196, s55, v78
	v_add_co_u32_e32 v78, vcc, s9, v82
	v_lshlrev_b32_e32 v175, 1, v79
	s_nop 0
	v_addc_co_u32_e32 v79, vcc, 0, v83, vcc
	s_mov_b32 s9, 0x10e28000
	v_mfma_f32_32x32x16_bf16 v[34:49], v[102:105], v[72:75], v[34:49]
	v_add3_u32 v198, 0, v177, v175
	v_lshlrev_b64 v[76:77], 10, v[100:101]
	v_lshl_add_u64 v[76:77], s[12:13], 0, v[76:77]
	v_or_b32_e32 v76, s72, v76
	v_lshl_add_u64 v[100:101], v[76:77], 0, v[156:157]
	v_lshl_add_u64 v[100:101], s[2:3], 0, v[100:101]
	s_mov_b64 s[2:3], 0x12e38000
	v_mfma_f32_32x32x16_bf16 v[84:99], v[110:113], v[72:75], v[84:99]
	v_add_u32_e32 v197, 0xd800, v198
	v_mfma_f32_32x32x16_bf16 v[2:17], v[68:71], v[72:75], v[2:17]
	v_add_co_u32_e32 v72, vcc, s9, v82
	s_mov_b32 s9, 0x12e10000
	s_nop 0
	v_addc_co_u32_e32 v73, vcc, 0, v83, vcc
	v_add_co_u32_e32 v74, vcc, s9, v82
	s_mov_b32 s9, 0x12e18000
	s_nop 0
	v_addc_co_u32_e32 v75, vcc, 0, v83, vcc
	ds_read_b128 v[68:71], v174 offset:8800
	v_mfma_f32_32x32x16_bf16 v[18:33], v[58:61], v[62:65], v[18:33]
	v_add_co_u32_e32 v58, vcc, s9, v82
	s_mov_b32 s9, -1
	s_nop 0
	v_addc_co_u32_e32 v59, vcc, 0, v83, vcc
	global_load_dwordx4 v[104:107], v[78:79], off
	global_load_dwordx4 v[108:111], v[72:73], off
	global_load_dwordx4 v[112:115], v[74:75], off
	global_load_dwordx4 v[116:119], v[58:59], off
	s_waitcnt lgkmcnt(0)
	v_mfma_f32_32x32x16_bf16 v[34:49], v[68:71], v[62:65], v[34:49]
	ds_read_b64_tr_b16 v[58:59], v198 offset:17408
	ds_read_b64_tr_b16 v[68:69], v198 offset:17472
	ds_read_b64_tr_b16 v[72:73], v198 offset:17536
	ds_read_b64_tr_b16 v[120:121], v198 offset:17600
	ds_read_b64_tr_b16 v[60:61], v198 offset:19968
	ds_read_b64_tr_b16 v[70:71], v198 offset:20032
	ds_read_b64_tr_b16 v[74:75], v198 offset:20096
	ds_read_b64_tr_b16 v[122:123], v198 offset:20160
	ds_read_b64_tr_b16 v[76:77], v198 offset:22528
	ds_read_b64_tr_b16 v[124:125], v198 offset:22592
	ds_read_b64_tr_b16 v[128:129], v198 offset:22656
	ds_read_b64_tr_b16 v[132:133], v198 offset:22720
	ds_read_b64_tr_b16 v[78:79], v198 offset:25088
	ds_read_b64_tr_b16 v[126:127], v198 offset:25152
	ds_read_b64_tr_b16 v[130:131], v198 offset:25216
	ds_read_b64_tr_b16 v[134:135], v198 offset:25280
	v_mfma_f32_32x32x16_bf16 v[2:17], v[50:53], v[62:65], v[2:17]
	v_max_f32_e32 v50, v19, v19
	v_max_f32_e32 v51, v18, v18
	v_max_f32_e32 v50, v51, v50
	v_max3_f32 v52, v20, v21, v35
	v_max3_f32 v50, v50, v34, v36
	v_max3_f32 v51, v52, v24, v25
	v_max3_f32 v50, v50, v37, v22
	v_max3_f32 v51, v51, v40, v41
	v_max3_f32 v50, v50, v23, v38
	v_max3_f32 v51, v51, v28, v29
	v_max3_f32 v50, v50, v39, v26
	v_max3_f32 v51, v51, v44, v45
	v_max3_f32 v50, v50, v27, v42
	v_max3_f32 v51, v51, v32, v33
	v_max3_f32 v50, v50, v43, v30
	v_max3_f32 v51, v51, v48, v49
	v_max3_f32 v50, v50, v31, v46
	v_max3_f32 v50, v50, v47, v51
	v_mov_b32_e32 v51, v50
	s_nop 1
	v_permlane32_swap_b32_e32 v50, v51
	v_max_f32_e32 v51, v51, v51
	v_max_f32_e32 v50, v50, v50
	v_max_f32_e32 v158, v50, v51
	v_sub_f32_e32 v18, v18, v158
	v_sub_f32_e32 v19, v19, v158
	v_sub_f32_e32 v20, v20, v158
	v_sub_f32_e32 v21, v21, v158
	v_sub_f32_e32 v22, v22, v158
	v_sub_f32_e32 v23, v23, v158
	v_sub_f32_e32 v24, v24, v158
	v_sub_f32_e32 v25, v25, v158
	v_exp_f32_e32 v102, v18
	v_exp_f32_e32 v178, v19
	v_exp_f32_e32 v182, v20
	v_exp_f32_e32 v184, v21
	v_exp_f32_e32 v190, v22
	v_exp_f32_e32 v192, v23
	v_exp_f32_e32 v204, v24
	v_exp_f32_e32 v206, v25
	v_cvt_pk_bf16_f32 v136, v102, v178
	v_cvt_pk_bf16_f32 v137, v182, v184
	v_cvt_pk_bf16_f32 v138, v190, v192
	v_cvt_pk_bf16_f32 v139, v204, v206
	v_sub_f32_e32 v26, v26, v158
	v_sub_f32_e32 v27, v27, v158
	v_sub_f32_e32 v28, v28, v158
	v_sub_f32_e32 v29, v29, v158
	v_sub_f32_e32 v30, v30, v158
	v_sub_f32_e32 v31, v31, v158
	v_sub_f32_e32 v18, v32, v158
	v_sub_f32_e32 v19, v33, v158
	v_exp_f32_e32 v208, v26
	v_exp_f32_e32 v210, v27
	v_exp_f32_e32 v212, v28
	v_exp_f32_e32 v214, v29
	v_exp_f32_e32 v226, v30
	v_exp_f32_e32 v228, v31
	v_exp_f32_e32 v232, v18
	v_exp_f32_e32 v234, v19
	v_mfma_f32_32x32x16_bf16 v[84:99], v[54:57], v[62:65], v[84:99]
	v_cvt_pk_bf16_f32 v140, v208, v210
	v_cvt_pk_bf16_f32 v141, v212, v214
	v_cvt_pk_bf16_f32 v142, v226, v228
	v_cvt_pk_bf16_f32 v143, v232, v234
	v_sub_f32_e32 v159, v36, v158
	v_sub_f32_e32 v67, v34, v158
	v_sub_f32_e32 v157, v35, v158
	s_waitcnt lgkmcnt(0)
; __device__ __forceinline__ unsigned cvt_pk_bf16(float lo, float hi) { const f32x2 v = {lo, hi}; const bf16x2_t b = __builtin_convertvector(v, bf16x2_t); return __builtin_bit_cast(unsigned, b); }
; __device__ __forceinline__ float fast_exp2(float x) { return __builtin_amdgcn_exp2f(x); }
; template <int NDT, int VSTR> ...
;     ...
;     for (int r = 0; r < 16; ++r) { p0[r] = fast_exp2(p0[r]); p1[r] = fast_exp2(p1[r]); rs0 += p0[r]; rs1 += p1[r]; }
;     lrun += rs0 + rs1;
;     bf16x8 pa[4];
; #pragma unroll
;     for (int s = 0; s < 2; ++s) {
;         u32x4 w0, w1;
;         w0.x = cvt_pk_bf16(p0[8 * s + 0], p0[8 * s + 1]); w0.y = cvt_pk_bf16(p0[8 * s + 2], p0[8 * s + 3]); w0.z = cvt_pk_bf16(p0[8 * s + 4], p0[8 * s + 5]); w0.w = cvt_pk_bf16(p0[8 * s + 6], p0[8 * s + 7]);
;         w1.x = cvt_pk_bf16(p1[8 * s + 0], p1[8 * s + 1]); w1.y = cvt_pk_bf16(p1[8 * s + 2], p1[8 * s + 3]); w1.z = cvt_pk_bf16(p1[8 * s + 4], p1[8 * s + 5]); w1.w = cvt_pk_bf16(p1[8 * s + 6], p1[8 * s + 7]);
;         pa[s] = __builtin_bit_cast(bf16x8, w0); pa[2 + s] = __builtin_bit_cast(bf16x8, w1);
;     }
; #pragma unroll
;     for (int s = 0; s < 4; ++s) {
;         bf16x8 vw[NDT];
; #pragma unroll
;         for (int d = 0; d < NDT; ++d) { if (s < PRE) vw[d] = vpre[s < PRE ? s : 0][d]; else vw[d] = VFRAG(s, d); }
; #pragma unroll
;         for (int d = 0; d < NDT; ++d) o[d] = __builtin_amdgcn_mfma_f32_32x32x16_bf16(pa[s], vw[d], o[d], 0, 0, 0);
;     }
; __device__ __forceinline__ void diff_unit(const Params& P, int l, int b, int h, int qb, float lam, float lam_init, LAS unsigned char* lds, bool dry = false) {
;     ...
;     DIFF_ITER(0, s0, s1, n0, n1);
;     int t = 1;
;     float rmc = 0.f;
;     if (t + 1 <= NT - 6) rmc = rowmax32(n0, n1);
	v_mfma_f32_32x32x16_bf16 v[50:65], v[136:139], v[58:61], 0
	v_sub_f32_e32 v185, v37, v158
	v_sub_f32_e32 v191, v38, v158
	v_sub_f32_e32 v193, v39, v158
	v_sub_f32_e32 v205, v40, v158
	v_sub_f32_e32 v207, v41, v158
	v_sub_f32_e32 v209, v42, v158
	v_sub_f32_e32 v211, v43, v158
	v_sub_f32_e32 v213, v44, v158
	v_sub_f32_e32 v215, v45, v158
	v_sub_f32_e32 v227, v46, v158
	v_sub_f32_e32 v229, v47, v158
	v_sub_f32_e32 v231, v48, v158
	v_sub_f32_e32 v235, v49, v158
	v_mfma_f32_32x32x16_bf16 v[34:49], v[136:139], v[68:71], 0
	v_add_f32_e64 v68, v2, -v158
	v_add_f32_e64 v69, v3, -v158
	v_add_f32_e64 v70, v4, -v158
	v_add_f32_e64 v71, v5, -v158
	v_add_f32_e64 v80, v14, -v158
	v_add_f32_e64 v81, v15, -v158
	v_pk_add_f32 v[82:83], v[16:17], v[158:159] op_sel_hi:[1,0] neg_lo:[0,1] neg_hi:[0,1]
	v_exp_f32_e32 v103, v67
	v_exp_f32_e32 v179, v157
	v_exp_f32_e32 v183, v159
	v_mfma_f32_32x32x16_bf16 v[18:33], v[136:139], v[72:75], 0
	v_add_f32_e64 v72, v6, -v158
	v_add_f32_e64 v73, v7, -v158
	v_add_f32_e64 v74, v8, -v158
	v_add_f32_e64 v75, v9, -v158
	v_exp_f32_e32 v185, v185
	v_exp_f32_e32 v191, v191
	v_exp_f32_e32 v193, v193
	v_exp_f32_e32 v205, v205
	v_exp_f32_e32 v207, v207
	v_mfma_f32_32x32x16_bf16 v[50:65], v[140:143], v[76:79], v[50:65]
	v_add_f32_e64 v76, v10, -v158
	v_add_f32_e64 v77, v11, -v158
	v_add_f32_e64 v78, v12, -v158
	v_add_f32_e64 v79, v13, -v158
	v_add_f32_e64 v84, v84, -v158
	v_add_f32_e64 v85, v85, -v158
	v_pk_add_f32 v[86:87], v[86:87], v[158:159] op_sel_hi:[1,0] neg_lo:[0,1] neg_hi:[0,1]
	v_max_f32_e32 v67, v84, v85
	v_pk_add_f32 v[88:89], v[88:89], v[158:159] op_sel_hi:[1,0] neg_lo:[0,1] neg_hi:[0,1]
	v_pk_add_f32 v[90:91], v[90:91], v[158:159] op_sel_hi:[1,0] neg_lo:[0,1] neg_hi:[0,1]
	v_mfma_f32_32x32x16_bf16 v[2:17], v[136:139], v[120:123], 0
	v_cvt_pk_bf16_f32 v120, v103, v179
	v_cvt_pk_bf16_f32 v121, v183, v185
	v_cvt_pk_bf16_f32 v122, v191, v193
	v_cvt_pk_bf16_f32 v123, v205, v207
	v_max3_f32 v67, v67, v68, v70
	v_max3_f32 v67, v67, v71, v88
	v_pk_add_f32 v[92:93], v[92:93], v[158:159] op_sel_hi:[1,0] neg_lo:[0,1] neg_hi:[0,1]
	v_mfma_f32_32x32x16_bf16 v[34:49], v[140:143], v[124:127], v[34:49]
	ds_read_b64_tr_b16 v[124:125], v198 offset:27648
	ds_read_b64_tr_b16 v[144:145], v198 offset:27712
	ds_read_b64_tr_b16 v[148:149], v198 offset:27776
	ds_read_b64_tr_b16 v[152:153], v198 offset:27840
	ds_read_b64_tr_b16 v[126:127], v198 offset:30208
	ds_read_b64_tr_b16 v[146:147], v198 offset:30272
	ds_read_b64_tr_b16 v[150:151], v198 offset:30336
	ds_read_b64_tr_b16 v[154:155], v198 offset:30400
	v_pk_add_f32 v[94:95], v[94:95], v[158:159] op_sel_hi:[1,0] neg_lo:[0,1] neg_hi:[0,1]
	v_max3_f32 v67, v67, v89, v72
	v_pk_add_f32 v[102:103], v[102:103], 0 op_sel_hi:[1,0]
	v_max3_f32 v67, v67, v73, v92
	v_pk_add_f32 v[102:103], v[178:179], v[102:103]
	v_pk_add_f32 v[96:97], v[96:97], v[158:159] op_sel_hi:[1,0] neg_lo:[0,1] neg_hi:[0,1]
	v_mfma_f32_32x32x16_bf16 v[18:33], v[140:143], v[128:131], v[18:33]
	v_add_f32_e64 v98, v98, -v158
	v_add_f32_e64 v99, v99, -v158
	v_exp_f32_e32 v209, v209
	v_exp_f32_e32 v211, v211
	v_exp_f32_e32 v213, v213
	v_exp_f32_e32 v215, v215
	v_exp_f32_e32 v227, v227
	v_exp_f32_e32 v229, v229
	v_mfma_f32_32x32x16_bf16 v[2:17], v[140:143], v[132:135], v[2:17]
	v_max3_f32 v132, v86, v87, v69
	v_exp_f32_e32 v233, v231
	v_exp_f32_e32 v235, v235
	v_max3_f32 v67, v67, v93, v76
	v_pk_add_f32 v[102:103], v[182:183], v[102:103]
	v_max3_f32 v67, v67, v77, v96
	v_pk_add_f32 v[102:103], v[184:185], v[102:103]
	s_waitcnt lgkmcnt(0)
	v_mfma_f32_32x32x16_bf16 v[50:65], v[120:123], v[124:127], v[50:65]
	v_max3_f32 v124, v132, v90, v91
	v_max3_f32 v124, v124, v74, v75
	v_max3_f32 v132, v124, v94, v95
	v_max3_f32 v132, v132, v78, v79
	v_max3_f32 v132, v132, v98, v99
	v_max3_f32 v132, v132, v82, v83
	v_max3_f32 v67, v67, v97, v80
	v_mfma_f32_32x32x16_bf16 v[34:49], v[120:123], v[144:147], v[34:49]
	v_add_f32_e64 v102, v190, v102
	v_add_f32_e64 v103, v191, v103
	v_max3_f32 v67, v67, v81, v132
	v_add_f32_e64 v102, v192, v102
	v_add_f32_e64 v103, v193, v103
	ds_read_b64_tr_b16 v[128:129], v198 offset:32768
	ds_read_b64_tr_b16 v[164:165], v198 offset:32832
	ds_read_b64_tr_b16 v[168:169], v198 offset:32896
	ds_read_b64_tr_b16 v[200:201], v198 offset:32960
	ds_read_b64_tr_b16 v[130:131], v198 offset:35328
	ds_read_b64_tr_b16 v[166:167], v198 offset:35392
	ds_read_b64_tr_b16 v[170:171], v198 offset:35456
	ds_read_b64_tr_b16 v[202:203], v198 offset:35520
	v_cvt_pk_bf16_f32 v124, v209, v211
	v_cvt_pk_bf16_f32 v125, v213, v215
	v_cvt_pk_bf16_f32 v126, v227, v229
	v_mfma_f32_32x32x16_bf16 v[18:33], v[120:123], v[148:151], v[18:33]
	v_cvt_pk_bf16_f32 v127, v233, v235
	v_add_f32_e64 v102, v204, v102
	v_add_f32_e64 v103, v205, v103
	s_waitcnt vmcnt(0)
	ds_write_b128 v163, v[104:107]
	ds_write_b128 v163, v[108:111] offset:8704
	ds_write_b128 v172, v[112:115] offset:55296
	ds_write_b128 v173, v[116:119] offset:55296
	v_pk_add_f32 v[102:103], v[206:207], v[102:103]
	s_waitcnt lgkmcnt(0)
	s_barrier
	v_mfma_f32_32x32x16_bf16 v[2:17], v[120:123], v[152:155], v[2:17]
	v_mov_b32_e32 v120, v67
	s_nop 1
	v_permlane32_swap_b32_e32 v67, v120
	v_max_f32_e32 v122, v120, v120
	v_add_f32_e64 v120, v208, v102
	v_add_f32_e64 v121, v209, v103
	v_max_f32_e32 v67, v67, v67
	v_pk_add_f32 v[120:121], v[210:211], v[120:121]
	v_mfma_f32_32x32x16_bf16 v[50:65], v[124:127], v[128:131], v[50:65]
	v_add_f32_e64 v120, v212, v120
	v_add_f32_e64 v121, v213, v121
	v_max_f32_e32 v102, v67, v122
	v_add_f32_e64 v120, v214, v120
	v_add_f32_e64 v121, v215, v121
	v_sub_u32_e32 v67, s70, v195
	v_pk_add_f32 v[120:121], v[226:227], v[120:121]
	v_add_u32_e32 v67, 0xffffff80, v67
	v_pk_add_f32 v[120:121], v[228:229], v[120:121]
	v_mfma_f32_32x32x16_bf16 v[34:49], v[124:127], v[164:167], v[34:49]
	v_add_f32_e64 v120, v232, v120
	v_add_f32_e64 v121, v233, v121
	v_add_f32_e64 v120, v234, v120
	v_add_f32_e64 v121, v235, v121
	v_pk_add_f32 v[120:121], v[120:121], v[120:121] op_sel:[0,1] op_sel_hi:[1,0]
	s_nop 0
	v_mov_b32_e32 v121, v158
	v_mfma_f32_32x32x16_bf16 v[18:33], v[124:127], v[168:171], v[18:33]
	v_lshl_add_u64 v[158:159], v[100:101], 0, s[2:3]
	s_mov_b64 s[2:3], 0x10e50000
	v_add_f32_e64 v190, v120, 0
	v_add_f32_e64 v191, v121, 0
	v_lshl_add_u64 v[192:193], v[100:101], 0, s[2:3]
	v_mfma_f32_32x32x16_bf16 v[2:17], v[124:127], v[200:203], v[2:17]
